# per-unit accumulator zeroing with v_mov_b64 (64 instead of 128 VALU per wave per unit) on top of the sample-context pipelining
# speedup vs baseline: 1.0240x; 1.0070x over previous
; template <class Epi, class Sched, bool ALIGN_EPI = false, bool SP2 = false>
; __device__ __forceinline__ void gemm_phase(PG8_LAS unsigned char* lds, const Gemm g, const Sched& S, const Epi& E, const int tid) {
;     ...
;         const char* nA = has_next ? (const char*)g.A + (size_t)nxt.pm * tstepA + (size_t)nxt.pn * g.a_pn_bytes : cA; const char* nB = has_next ? (const char*)g.Bt + (size_t)nxt.pn * tstepB : cB;
;         for (int t = 0; t < nt; t += 2) {
;             const bool last = (t == nt - 2);
;             const char* a1 = cA + (size_t)(t + 1) * kstep;
;             const char* a2 = last ? nA : cA + (size_t)(t + 2) * kstep; const char* b2 = last ? nB : cB + (size_t)(t + 2) * kstep;
;             const char* a3 = a2 + kstep; const char* b3 = b2 + kstep;
;     ...
; #pragma unroll
;         for (int a = 0; a < 2; ++a)
; #pragma unroll
;             for (int b = 0; b < 2; ++b)
; #pragma unroll
;                 for (int m = 0; m < 4; ++m)
; #pragma unroll
;                     for (int n = 0; n < 2; ++n) acc[a][b][m][n] = (f32x4){0.f, 0.f, 0.f, 0.f};
;         cur = nxt; cA = nA; cB = nB; ++ui;
.LBB0_549:
	s_ashr_i32 s89, s88, 31
	s_lshl_b64 s[34:35], s[88:89], 19
	s_add_u32 s92, s1, s34
	s_addc_u32 s93, s3, s35
	s_and_b64 s[34:35], s[90:91], exec
	s_cselect_b32 s7, s93, s23
	s_cselect_b32 s58, s92, s22
	s_ashr_i32 s87, s86, 31
	s_lshl_b64 s[34:35], s[86:87], 19
	s_add_u32 s94, s4, s34
	s_addc_u32 s95, s5, s35
	s_and_b64 s[34:35], s[90:91], exec
	s_cselect_b32 s59, s95, s11
	s_cselect_b32 s73, s94, s10
	s_add_u32 s78, s10, 0x100
	s_addc_u32 s79, s11, 0
	s_add_u32 s10, s22, 0x40080
	s_addc_u32 s11, s23, 0
	s_mov_b32 s87, -2
	v_mov_b64_e32 v[0:1], 0
	v_mov_b64_e32 v[2:3], 0
	v_mov_b64_e32 v[4:5], 0
	v_mov_b64_e32 v[6:7], 0
	v_mov_b64_e32 v[8:9], 0
	v_mov_b64_e32 v[10:11], 0
	v_mov_b64_e32 v[12:13], 0
	v_mov_b64_e32 v[14:15], 0
	v_mov_b64_e32 v[16:17], 0
	v_mov_b64_e32 v[18:19], 0
	v_mov_b64_e32 v[20:21], 0
	v_mov_b64_e32 v[22:23], 0
	v_mov_b64_e32 v[24:25], 0
	v_mov_b64_e32 v[26:27], 0
	v_mov_b64_e32 v[28:29], 0
	v_mov_b64_e32 v[30:31], 0
	v_mov_b64_e32 v[32:33], 0
	v_mov_b64_e32 v[34:35], 0
	v_mov_b64_e32 v[36:37], 0
	v_mov_b64_e32 v[38:39], 0
	v_mov_b64_e32 v[40:41], 0
	v_mov_b64_e32 v[42:43], 0
	v_mov_b64_e32 v[44:45], 0
	v_mov_b64_e32 v[46:47], 0
	v_mov_b64_e32 v[48:49], 0
	v_mov_b64_e32 v[50:51], 0
	v_mov_b64_e32 v[52:53], 0
	v_mov_b64_e32 v[54:55], 0
	v_mov_b64_e32 v[56:57], 0
	v_mov_b64_e32 v[58:59], 0
	v_mov_b64_e32 v[60:61], 0
	v_mov_b64_e32 v[62:63], 0
	v_mov_b64_e32 v[64:65], 0
	v_mov_b64_e32 v[66:67], 0
	v_mov_b64_e32 v[68:69], 0
	v_mov_b64_e32 v[70:71], 0
	v_mov_b64_e32 v[72:73], 0
	v_mov_b64_e32 v[74:75], 0
	v_mov_b64_e32 v[76:77], 0
	v_mov_b64_e32 v[78:79], 0
	v_mov_b64_e32 v[80:81], 0
	v_mov_b64_e32 v[82:83], 0
	v_mov_b64_e32 v[84:85], 0
	v_mov_b64_e32 v[86:87], 0
	v_mov_b64_e32 v[88:89], 0
	v_mov_b64_e32 v[90:91], 0
	v_mov_b64_e32 v[124:125], 0
	v_mov_b64_e32 v[126:127], 0
	v_mov_b64_e32 v[128:129], 0
	v_mov_b64_e32 v[130:131], 0
	v_mov_b64_e32 v[132:133], 0
	v_mov_b64_e32 v[134:135], 0
	v_mov_b64_e32 v[136:137], 0
	v_mov_b64_e32 v[138:139], 0
	v_mov_b64_e32 v[140:141], 0
	v_mov_b64_e32 v[142:143], 0
	v_mov_b64_e32 v[144:145], 0
	v_mov_b64_e32 v[146:147], 0
	v_mov_b64_e32 v[148:149], 0
	v_mov_b64_e32 v[150:151], 0
	v_mov_b64_e32 v[152:153], 0
	v_mov_b64_e32 v[154:155], 0
	v_mov_b64_e32 v[156:157], 0
	v_mov_b64_e32 v[158:159], 0

; template <class Epi, class Sched, bool ALIGN_EPI = false, bool SP2 = false>
; __device__ __forceinline__ void gemm_phase(PG8_LAS unsigned char* lds, const Gemm g, const Sched& S, const Epi& E, const int tid) {
;     ...
; #pragma unroll
;         for (int a = 0; a < 2; ++a)
; #pragma unroll
;             for (int b = 0; b < 2; ++b)
; #pragma unroll
;                 for (int m = 0; m < 4; ++m)
; #pragma unroll
;                     for (int n = 0; n < 2; ++n) acc[a][b][m][n] = (f32x4){0.f, 0.f, 0.f, 0.f};
;         cur = nxt; cA = nA; cB = nB; ++ui;
.LBB0_913:
	s_add_u32 s60, s30, 0x100
	s_addc_u32 s61, s31, 0
	s_mov_b32 s62, -2
	v_mov_b64_e32 v[0:1], 0
	v_mov_b64_e32 v[2:3], 0
	v_mov_b64_e32 v[4:5], 0
	v_mov_b64_e32 v[6:7], 0
	v_mov_b64_e32 v[8:9], 0
	v_mov_b64_e32 v[10:11], 0
	v_mov_b64_e32 v[12:13], 0
	v_mov_b64_e32 v[14:15], 0
	v_mov_b64_e32 v[16:17], 0
	v_mov_b64_e32 v[18:19], 0
	v_mov_b64_e32 v[20:21], 0
	v_mov_b64_e32 v[22:23], 0
	v_mov_b64_e32 v[24:25], 0
	v_mov_b64_e32 v[26:27], 0
	v_mov_b64_e32 v[28:29], 0
	v_mov_b64_e32 v[30:31], 0
	v_mov_b64_e32 v[32:33], 0
	v_mov_b64_e32 v[34:35], 0
	v_mov_b64_e32 v[36:37], 0
	v_mov_b64_e32 v[38:39], 0
	v_mov_b64_e32 v[40:41], 0
	v_mov_b64_e32 v[42:43], 0
	v_mov_b64_e32 v[44:45], 0
	v_mov_b64_e32 v[46:47], 0
	v_mov_b64_e32 v[48:49], 0
	v_mov_b64_e32 v[50:51], 0
	v_mov_b64_e32 v[52:53], 0
	v_mov_b64_e32 v[54:55], 0
	v_mov_b64_e32 v[56:57], 0
	v_mov_b64_e32 v[58:59], 0
	v_mov_b64_e32 v[60:61], 0
	v_mov_b64_e32 v[62:63], 0
	v_mov_b64_e32 v[64:65], 0
	v_mov_b64_e32 v[66:67], 0
	v_mov_b64_e32 v[68:69], 0
	v_mov_b64_e32 v[70:71], 0
	v_mov_b64_e32 v[72:73], 0
	v_mov_b64_e32 v[74:75], 0
	v_mov_b64_e32 v[76:77], 0
	v_mov_b64_e32 v[78:79], 0
	v_mov_b64_e32 v[80:81], 0
	v_mov_b64_e32 v[82:83], 0
	v_mov_b64_e32 v[84:85], 0
	v_mov_b64_e32 v[86:87], 0
	v_mov_b64_e32 v[88:89], 0
	v_mov_b64_e32 v[90:91], 0
	v_mov_b64_e32 v[92:93], 0
	v_mov_b64_e32 v[94:95], 0
	v_mov_b64_e32 v[96:97], 0
	v_mov_b64_e32 v[98:99], 0
	v_mov_b64_e32 v[100:101], 0
	v_mov_b64_e32 v[102:103], 0
	v_mov_b64_e32 v[104:105], 0
	v_mov_b64_e32 v[106:107], 0
	v_mov_b64_e32 v[108:109], 0
	v_mov_b64_e32 v[110:111], 0
	v_mov_b64_e32 v[112:113], 0
	v_mov_b64_e32 v[114:115], 0
	v_mov_b64_e32 v[116:117], 0
	v_mov_b64_e32 v[118:119], 0
	v_mov_b64_e32 v[120:121], 0
	v_mov_b64_e32 v[122:123], 0
	v_mov_b64_e32 v[124:125], 0
	v_mov_b64_e32 v[126:127], 0

; template <class Epi, class Sched, bool ALIGN_EPI = false, bool SP2 = false>
; __device__ __forceinline__ void gemm_phase(PG8_LAS unsigned char* lds, const Gemm g, const Sched& S, const Epi& E, const int tid) {
;     ...
;         const char* nA = has_next ? (const char*)g.A + (size_t)nxt.pm * tstepA + (size_t)nxt.pn * g.a_pn_bytes : cA; const char* nB = has_next ? (const char*)g.Bt + (size_t)nxt.pn * tstepB : cB;
;         for (int t = 0; t < nt; t += 2) {
;             const bool last = (t == nt - 2);
;             const char* a1 = cA + (size_t)(t + 1) * kstep;
;             const char* a2 = last ? nA : cA + (size_t)(t + 2) * kstep; const char* b2 = last ? nB : cB + (size_t)(t + 2) * kstep;
;             const char* a3 = a2 + kstep; const char* b3 = b2 + kstep;
;     ...
; #pragma unroll
;         for (int a = 0; a < 2; ++a)
; #pragma unroll
;             for (int b = 0; b < 2; ++b)
; #pragma unroll
;                 for (int m = 0; m < 4; ++m)
; #pragma unroll
;                     for (int n = 0; n < 2; ++n) acc[a][b][m][n] = (f32x4){0.f, 0.f, 0.f, 0.f};
;         cur = nxt; cA = nA; cB = nB; ++ui;
.LBB0_1245:
	s_ashr_i32 s43, s42, 31
	s_lshl_b64 s[44:45], s[42:43], 19
	s_add_u32 s44, s3, s44
	s_addc_u32 s45, s4, s45
	s_and_b64 s[46:47], s[12:13], exec
	s_cselect_b32 s43, s45, s7
	s_cselect_b32 s58, s44, s6
	s_ashr_i32 s41, s40, 31
	s_lshl_b64 s[46:47], s[40:41], 19
	s_add_u32 s46, s5, s46
	s_addc_u32 s47, s33, s47
	s_and_b64 s[50:51], s[12:13], exec
	s_cselect_b32 s41, s47, s49
	s_cselect_b32 s59, s46, s48
	s_add_u32 s6, s6, 0x40080
	s_addc_u32 s7, s7, 0
	s_add_u32 s72, s48, 0x100
	s_addc_u32 s73, s49, 0
	s_mov_b32 s74, -2
	v_mov_b64_e32 v[0:1], 0
	v_mov_b64_e32 v[2:3], 0
	v_mov_b64_e32 v[4:5], 0
	v_mov_b64_e32 v[6:7], 0
	v_mov_b64_e32 v[8:9], 0
	v_mov_b64_e32 v[10:11], 0
	v_mov_b64_e32 v[12:13], 0
	v_mov_b64_e32 v[14:15], 0
	v_mov_b64_e32 v[16:17], 0
	v_mov_b64_e32 v[18:19], 0
	v_mov_b64_e32 v[20:21], 0
	v_mov_b64_e32 v[22:23], 0
	v_mov_b64_e32 v[24:25], 0
	v_mov_b64_e32 v[26:27], 0
	v_mov_b64_e32 v[28:29], 0
	v_mov_b64_e32 v[30:31], 0
	v_mov_b64_e32 v[32:33], 0
	v_mov_b64_e32 v[34:35], 0
	v_mov_b64_e32 v[36:37], 0
	v_mov_b64_e32 v[38:39], 0
	v_mov_b64_e32 v[40:41], 0
	v_mov_b64_e32 v[42:43], 0
	v_mov_b64_e32 v[44:45], 0
	v_mov_b64_e32 v[46:47], 0
	v_mov_b64_e32 v[48:49], 0
	v_mov_b64_e32 v[50:51], 0
	v_mov_b64_e32 v[52:53], 0
	v_mov_b64_e32 v[54:55], 0
	v_mov_b64_e32 v[56:57], 0
	v_mov_b64_e32 v[58:59], 0
	v_mov_b64_e32 v[60:61], 0
	v_mov_b64_e32 v[62:63], 0
	v_mov_b64_e32 v[64:65], 0
	v_mov_b64_e32 v[66:67], 0
	v_mov_b64_e32 v[68:69], 0
	v_mov_b64_e32 v[70:71], 0
	v_mov_b64_e32 v[72:73], 0
	v_mov_b64_e32 v[74:75], 0
	v_mov_b64_e32 v[76:77], 0
	v_mov_b64_e32 v[78:79], 0
	v_mov_b64_e32 v[80:81], 0
	v_mov_b64_e32 v[82:83], 0
	v_mov_b64_e32 v[84:85], 0
	v_mov_b64_e32 v[86:87], 0
	v_mov_b64_e32 v[88:89], 0
	v_mov_b64_e32 v[90:91], 0
	v_mov_b64_e32 v[92:93], 0
	v_mov_b64_e32 v[94:95], 0
	v_mov_b64_e32 v[96:97], 0
	v_mov_b64_e32 v[98:99], 0
	v_mov_b64_e32 v[100:101], 0
	v_mov_b64_e32 v[102:103], 0
	v_mov_b64_e32 v[104:105], 0
	v_mov_b64_e32 v[106:107], 0
	v_mov_b64_e32 v[108:109], 0
	v_mov_b64_e32 v[110:111], 0
	v_mov_b64_e32 v[112:113], 0
	v_mov_b64_e32 v[114:115], 0
	v_mov_b64_e32 v[116:117], 0
	v_mov_b64_e32 v[118:119], 0
	v_mov_b64_e32 v[120:121], 0
	v_mov_b64_e32 v[122:123], 0
	v_mov_b64_e32 v[124:125], 0
	v_mov_b64_e32 v[126:127], 0

; template <class Epi, class Sched, bool ALIGN_EPI = false, bool SP2 = false>
; __device__ __forceinline__ void gemm_phase(PG8_LAS unsigned char* lds, const Gemm g, const Sched& S, const Epi& E, const int tid) {
;     ...
;         const char* nA = has_next ? (const char*)g.A + (size_t)nxt.pm * tstepA + (size_t)nxt.pn * g.a_pn_bytes : cA; const char* nB = has_next ? (const char*)g.Bt + (size_t)nxt.pn * tstepB : cB;
;         for (int t = 0; t < nt; t += 2) {
;             const bool last = (t == nt - 2);
;             const char* a1 = cA + (size_t)(t + 1) * kstep;
;             const char* a2 = last ? nA : cA + (size_t)(t + 2) * kstep; const char* b2 = last ? nB : cB + (size_t)(t + 2) * kstep;
;             const char* a3 = a2 + kstep; const char* b3 = b2 + kstep;
;     ...
; #pragma unroll
;         for (int a = 0; a < 2; ++a)
; #pragma unroll
;             for (int b = 0; b < 2; ++b)
; #pragma unroll
;                 for (int m = 0; m < 4; ++m)
; #pragma unroll
;                     for (int n = 0; n < 2; ++n) acc[a][b][m][n] = (f32x4){0.f, 0.f, 0.f, 0.f};
;         cur = nxt; cA = nA; cB = nB; ++ui;
.LBB0_1516:
	s_ashr_i32 s29, s28, 31
	s_lshl_b64 s[30:31], s[28:29], 19
	s_add_u32 s30, s3, s30
	s_addc_u32 s31, s4, s31
	s_and_b64 s[34:35], s[12:13], exec
	s_cselect_b32 s29, s31, s37
	s_cselect_b32 s60, s30, s36
	s_ashr_i32 s27, s26, 31
	s_lshl_b64 s[34:35], s[26:27], 19
	s_add_u32 s34, s5, s34
	s_addc_u32 s35, s33, s35
	s_and_b64 s[40:41], s[12:13], exec
	s_cselect_b32 s27, s35, s39
	s_cselect_b32 s61, s34, s38
	s_add_u32 s36, s36, 0x40080
	s_addc_u32 s37, s37, 0
	s_add_u32 s62, s38, 0x100
	s_addc_u32 s63, s39, 0
	s_mov_b32 s64, -2
	v_mov_b64_e32 v[0:1], 0
	v_mov_b64_e32 v[2:3], 0
	v_mov_b64_e32 v[4:5], 0
	v_mov_b64_e32 v[6:7], 0
	v_mov_b64_e32 v[8:9], 0
	v_mov_b64_e32 v[10:11], 0
	v_mov_b64_e32 v[12:13], 0
	v_mov_b64_e32 v[14:15], 0
	v_mov_b64_e32 v[16:17], 0
	v_mov_b64_e32 v[18:19], 0
	v_mov_b64_e32 v[20:21], 0
	v_mov_b64_e32 v[22:23], 0
	v_mov_b64_e32 v[24:25], 0
	v_mov_b64_e32 v[26:27], 0
	v_mov_b64_e32 v[28:29], 0
	v_mov_b64_e32 v[30:31], 0
	v_mov_b64_e32 v[32:33], 0
	v_mov_b64_e32 v[34:35], 0
	v_mov_b64_e32 v[36:37], 0
	v_mov_b64_e32 v[38:39], 0
	v_mov_b64_e32 v[40:41], 0
	v_mov_b64_e32 v[42:43], 0
	v_mov_b64_e32 v[44:45], 0
	v_mov_b64_e32 v[46:47], 0
	v_mov_b64_e32 v[48:49], 0
	v_mov_b64_e32 v[50:51], 0
	v_mov_b64_e32 v[52:53], 0
	v_mov_b64_e32 v[54:55], 0
	v_mov_b64_e32 v[56:57], 0
	v_mov_b64_e32 v[58:59], 0
	v_mov_b64_e32 v[60:61], 0
	v_mov_b64_e32 v[62:63], 0
	v_mov_b64_e32 v[64:65], 0
	v_mov_b64_e32 v[66:67], 0
	v_mov_b64_e32 v[68:69], 0
	v_mov_b64_e32 v[70:71], 0
	v_mov_b64_e32 v[72:73], 0
	v_mov_b64_e32 v[74:75], 0
	v_mov_b64_e32 v[76:77], 0
	v_mov_b64_e32 v[78:79], 0
	v_mov_b64_e32 v[80:81], 0
	v_mov_b64_e32 v[82:83], 0
	v_mov_b64_e32 v[84:85], 0
	v_mov_b64_e32 v[86:87], 0
	v_mov_b64_e32 v[88:89], 0
	v_mov_b64_e32 v[90:91], 0
	v_mov_b64_e32 v[92:93], 0
	v_mov_b64_e32 v[94:95], 0
	v_mov_b64_e32 v[96:97], 0
	v_mov_b64_e32 v[98:99], 0
	v_mov_b64_e32 v[100:101], 0
	v_mov_b64_e32 v[102:103], 0
	v_mov_b64_e32 v[104:105], 0
	v_mov_b64_e32 v[106:107], 0
	v_mov_b64_e32 v[108:109], 0
	v_mov_b64_e32 v[110:111], 0
	v_mov_b64_e32 v[112:113], 0
	v_mov_b64_e32 v[114:115], 0
	v_mov_b64_e32 v[116:117], 0
	v_mov_b64_e32 v[118:119], 0
	v_mov_b64_e32 v[120:121], 0
	v_mov_b64_e32 v[122:123], 0
	v_mov_b64_e32 v[124:125], 0
	v_mov_b64_e32 v[126:127], 0

; template <class Epi, class Sched, bool ALIGN_EPI = false, bool SP2 = false>
; __device__ __forceinline__ void gemm_phase(PG8_LAS unsigned char* lds, const Gemm g, const Sched& S, const Epi& E, const int tid) {
;     ...
;         const char* nA = has_next ? (const char*)g.A + (size_t)nxt.pm * tstepA + (size_t)nxt.pn * g.a_pn_bytes : cA; const char* nB = has_next ? (const char*)g.Bt + (size_t)nxt.pn * tstepB : cB;
;         for (int t = 0; t < nt; t += 2) {
;             const bool last = (t == nt - 2);
;             const char* a1 = cA + (size_t)(t + 1) * kstep;
;             const char* a2 = last ? nA : cA + (size_t)(t + 2) * kstep; const char* b2 = last ? nB : cB + (size_t)(t + 2) * kstep;
;             const char* a3 = a2 + kstep; const char* b3 = b2 + kstep;
;     ...
; #pragma unroll
;         for (int a = 0; a < 2; ++a)
; #pragma unroll
;             for (int b = 0; b < 2; ++b)
; #pragma unroll
;                 for (int m = 0; m < 4; ++m)
; #pragma unroll
;                     for (int n = 0; n < 2; ++n) acc[a][b][m][n] = (f32x4){0.f, 0.f, 0.f, 0.f};
;         cur = nxt; cA = nA; cB = nB; ++ui;
.LBB0_1667:
	s_ashr_i32 s87, s86, 31
	s_lshl_b64 s[58:59], s[86:87], 19
	s_add_u32 s90, s1, s58
	s_addc_u32 s91, s3, s59
	s_and_b64 s[58:59], s[88:89], exec
	s_cselect_b32 s7, s91, s23
	s_cselect_b32 s62, s90, s22
	s_ashr_i32 s85, s84, 31
	s_lshl_b64 s[58:59], s[84:85], 19
	s_add_u32 s92, s4, s58
	s_addc_u32 s93, s5, s59
	s_and_b64 s[58:59], s[88:89], exec
	s_cselect_b32 s63, s93, s9
	s_cselect_b32 s73, s92, s8
	s_add_u32 s85, s8, 0x100
	s_addc_u32 s87, s9, 0
	s_add_u32 s8, s22, 0x40080
	s_addc_u32 s9, s23, 0
	s_mov_b32 s94, -2
	v_mov_b64_e32 v[0:1], 0
	v_mov_b64_e32 v[2:3], 0
	v_mov_b64_e32 v[4:5], 0
	v_mov_b64_e32 v[6:7], 0
	v_mov_b64_e32 v[8:9], 0
	v_mov_b64_e32 v[10:11], 0
	v_mov_b64_e32 v[12:13], 0
	v_mov_b64_e32 v[14:15], 0
	v_mov_b64_e32 v[16:17], 0
	v_mov_b64_e32 v[18:19], 0
	v_mov_b64_e32 v[20:21], 0
	v_mov_b64_e32 v[22:23], 0
	v_mov_b64_e32 v[24:25], 0
	v_mov_b64_e32 v[26:27], 0
	v_mov_b64_e32 v[28:29], 0
	v_mov_b64_e32 v[30:31], 0
	v_mov_b64_e32 v[32:33], 0
	v_mov_b64_e32 v[34:35], 0
	v_mov_b64_e32 v[36:37], 0
	v_mov_b64_e32 v[38:39], 0
	v_mov_b64_e32 v[40:41], 0
	v_mov_b64_e32 v[42:43], 0
	v_mov_b64_e32 v[44:45], 0
	v_mov_b64_e32 v[46:47], 0
	v_mov_b64_e32 v[48:49], 0
	v_mov_b64_e32 v[50:51], 0
	v_mov_b64_e32 v[52:53], 0
	v_mov_b64_e32 v[54:55], 0
	v_mov_b64_e32 v[56:57], 0
	v_mov_b64_e32 v[58:59], 0
	v_mov_b64_e32 v[60:61], 0
	v_mov_b64_e32 v[62:63], 0
	v_mov_b64_e32 v[64:65], 0
	v_mov_b64_e32 v[66:67], 0
	v_mov_b64_e32 v[68:69], 0
	v_mov_b64_e32 v[70:71], 0
	v_mov_b64_e32 v[72:73], 0
	v_mov_b64_e32 v[74:75], 0
	v_mov_b64_e32 v[76:77], 0
	v_mov_b64_e32 v[78:79], 0
	v_mov_b64_e32 v[80:81], 0
	v_mov_b64_e32 v[82:83], 0
	v_mov_b64_e32 v[84:85], 0
	v_mov_b64_e32 v[86:87], 0
	v_mov_b64_e32 v[88:89], 0
	v_mov_b64_e32 v[90:91], 0
	v_mov_b64_e32 v[124:125], 0
	v_mov_b64_e32 v[126:127], 0
	v_mov_b64_e32 v[128:129], 0
	v_mov_b64_e32 v[130:131], 0
	v_mov_b64_e32 v[132:133], 0
	v_mov_b64_e32 v[134:135], 0
	v_mov_b64_e32 v[136:137], 0
	v_mov_b64_e32 v[138:139], 0
	v_mov_b64_e32 v[140:141], 0
	v_mov_b64_e32 v[142:143], 0
	v_mov_b64_e32 v[144:145], 0
	v_mov_b64_e32 v[146:147], 0
	v_mov_b64_e32 v[148:149], 0
	v_mov_b64_e32 v[150:151], 0
	v_mov_b64_e32 v[152:153], 0
	v_mov_b64_e32 v[154:155], 0
	v_mov_b64_e32 v[156:157], 0
	v_mov_b64_e32 v[158:159], 0
